# attention tile loop: writer-address toggles and exit compare rotated above the tile barrier
# speedup vs baseline: 1.0011x; 1.0011x over previous
; #define LAS __attribute__((address_space(3)))
; __device__ __forceinline__ void attn_phase(LAS unsigned char* ldsb, bf16_t* P, const bf16_t* Kn, const bf16_t* KPE, const bf16_t* VT) {
;     ...
;             for (int kt = 0; kt < nt; ++kt) {
;                 __syncthreads();
; #pragma unroll
;                 for (int i = 0; i < 3; ++i) { const int id = tid + 512 * i, row = id / 24, ch = id % 24; *(LAS u32x4*)(sK + row * 200 + ch * 8) = kst[i]; }
; #pragma unroll
;                 for (int i = 0; i < 2; ++i) { const int id = tid + 512 * i, d = id >> 3, ch = id & 7;
;                     *(LAS u32x2*)(sVt + d * 68 + ch * 8) = (u32x2){vst[i].x, vst[i].y}; *(LAS u32x2*)(sVt + d * 68 + ch * 8 + 4) = (u32x2){vst[i].z, vst[i].w}; }
;                 __syncthreads();
;                 if (kt + 1 < nt) ATT_LOAD(kt + 1);
.LBB0_1526:
	s_add_i32 s77, s77, -1
	s_add_i32 s78, s78, 64
	v_xor_b32_e32 v241, 0x10000, v241
	v_xor_b32_e32 v235, 0x10000, v235
	v_xor_b32_e32 v237, 0x10000, v237
	v_xor_b32_e32 v238, 0x10000, v238
	v_xor_b32_e32 v239, 0x10000, v239
	v_xor_b32_e32 v148, 0x10000, v148
	v_xor_b32_e32 v149, 0x10000, v149
	v_xor_b32_e32 v150, 0x10000, v150
	v_xor_b32_e32 v151, 0x10000, v151
	v_xor_b32_e32 v152, 0x10000, v152
	s_waitcnt lgkmcnt(0)
	s_cmp_eq_u32 s77, 0
	s_barrier
	s_cbranch_scc1 .Lattn_exit_w

; #define LAS __attribute__((address_space(3)))
; __device__ __forceinline__ void attn_phase(LAS unsigned char* ldsb, bf16_t* P, const bf16_t* Kn, const bf16_t* KPE, const bf16_t* VT) {
;     ...
;             for (int kt = 0; kt < nt; ++kt) {
;                 __syncthreads();
; #pragma unroll
;                 for (int i = 0; i < 3; ++i) { const int id = tid + 512 * i, row = id / 24, ch = id % 24; *(LAS u32x4*)(sK + row * 200 + ch * 8) = kst[i]; }
; #pragma unroll
;                 for (int i = 0; i < 2; ++i) { const int id = tid + 512 * i, d = id >> 3, ch = id & 7;
;                     *(LAS u32x2*)(sVt + d * 68 + ch * 8) = (u32x2){vst[i].x, vst[i].y}; *(LAS u32x2*)(sVt + d * 68 + ch * 8 + 4) = (u32x2){vst[i].z, vst[i].w}; }
;                 __syncthreads();
;                 if (kt + 1 < nt) ATT_LOAD(kt + 1);
.Lattn_exit_w:
	v_xor_b32_e32 v148, 0x10000, v148
	v_xor_b32_e32 v149, 0x10000, v149
	v_xor_b32_e32 v150, 0x10000, v150
	v_xor_b32_e32 v151, 0x10000, v151
	v_xor_b32_e32 v152, 0x10000, v152
	s_branch .LBB0_1532
